# stacked variant with GEMM K-loop heads padded to 64-byte boundaries
# speedup vs baseline: 1.0116x; 1.0048x over previous
.LBB0_223:
	v_add_u32_e32 v155, s81, v17
	v_add_u32_e32 v156, 0x2000, v155
	v_readfirstlane_b32 s17, v155
	v_lshl_add_u64 v[4:5], v[4:5], 0, s[6:7]
	s_mov_b32 m0, s17
	v_readfirstlane_b32 s17, v156
	v_add_u32_e32 v157, 0x8000, v148
	s_waitcnt vmcnt(4)
	s_barrier
	global_load_lds_dwordx4 v[4:5], off
	v_lshl_add_u64 v[4:5], v[6:7], 0, s[6:7]
	s_mov_b32 m0, s17
	v_readfirstlane_b32 s17, v157
	v_add_u32_e32 v158, 0xa000, v148
	global_load_lds_dwordx4 v[4:5], off
	v_lshl_add_u64 v[4:5], v[8:9], 0, s[6:7]
	s_mov_b32 m0, s17
	v_readfirstlane_b32 s17, v158
	v_add_u32_e32 v159, s82, v17
	global_load_lds_dwordx4 v[4:5], off
	v_lshl_add_u64 v[4:5], v[10:11], 0, s[6:7]
	s_mov_b32 m0, s17
	v_readfirstlane_b32 s17, v159
	v_add_u32_e32 v160, 0x2000, v159
	global_load_lds_dwordx4 v[4:5], off
	v_lshl_add_u64 v[4:5], v[12:13], 0, s[6:7]
	s_mov_b32 m0, s17
	v_readfirstlane_b32 s17, v160
	global_load_lds_dwordx4 v[4:5], off
	v_lshl_add_u64 v[4:5], v[14:15], 0, s[6:7]
	s_mov_b32 m0, s17
	v_and_b32_e32 v18, 15, v16
	global_load_lds_dwordx4 v[4:5], off
	v_lshlrev_b32_e32 v5, 2, v16
	v_and_b32_e32 v19, 48, v16
	v_lshlrev_b32_e32 v4, 6, v18
	v_and_b32_e32 v5, 32, v5
	v_bitop3_b32 v4, v4, v5, v19 bitop3:0x36
	v_add_u32_e32 v6, s33, v4
	v_add_u32_e32 v7, s80, v4
	v_add_u32_e32 v8, s81, v4
	v_add_u32_e32 v9, s82, v4
	s_lshl_b32 s60, s1, 13
	v_add_u32_e32 v10, 0, v4
	v_lshlrev_b32_e32 v4, 6, v16
	s_movk_i32 s1, 0x3c0
	v_and_or_b32 v4, v4, s1, v19
	v_xad_u32 v161, v4, v5, 0
	v_lshl_add_u64 v[4:5], s[24:25], 0, v[130:131]
	v_readlane_b32 s64, v254, 60
	v_lshl_add_u64 v[4:5], v[4:5], 0, v[0:1]
	v_readlane_b32 s76, v253, 8
	v_readlane_b32 s77, v253, 9
	v_readlane_b32 s65, v254, 61
	v_readlane_b32 s66, v254, 62
	v_lshl_add_u64 v[136:137], s[76:77], 0, v[4:5]
	v_lshl_add_u64 v[4:5], s[24:25], 0, v[134:135]
	v_readlane_b32 s67, v254, 63
	v_readlane_b32 s68, v253, 0
	v_readlane_b32 s69, v253, 1
	v_readlane_b32 s70, v253, 2
	v_readlane_b32 s71, v253, 3
	v_readlane_b32 s72, v253, 4
	v_readlane_b32 s73, v253, 5
	v_readlane_b32 s74, v253, 6
	v_readlane_b32 s75, v253, 7
	v_readlane_b32 s78, v253, 10
	v_readlane_b32 s79, v253, 11
	v_lshl_add_u64 v[4:5], v[4:5], 0, v[2:3]
	v_lshl_add_u64 v[138:139], s[76:77], 0, v[4:5]
	v_lshl_add_u64 v[4:5], s[34:35], 0, v[130:131]
	v_readlane_b32 s64, v254, 12
	v_lshl_add_u64 v[0:1], v[4:5], 0, v[0:1]
	v_readlane_b32 s68, v254, 16
	v_readlane_b32 s69, v254, 17
	s_waitcnt vmcnt(6)
	s_lshl_b32 s17, s88, 6
	s_and_b32 s59, s17, 0x3000
	v_lshl_add_u64 v[140:141], s[68:69], 0, v[0:1]
	v_lshl_add_u64 v[0:1], s[34:35], 0, v[134:135]
	v_lshl_add_u64 v[0:1], v[0:1], 0, v[2:3]
	v_lshl_add_u64 v[142:143], s[68:69], 0, v[0:1]
	v_mov_b32_e32 v0, 0
	s_or_b32 s1, s60, 0x800
	s_or_b32 s17, s60, 0x1000
	s_or_b32 s58, s60, 0x1800
	s_mov_b32 s34, -2
	s_mov_b64 s[24:25], 0
	v_add_u32_e32 v163, s59, v6
	v_add_u32_e32 v147, s60, v10
	v_add_u32_e32 v162, s59, v7
	v_add_u32_e32 v152, s59, v8
	v_add_u32_e32 v150, s59, v9
	v_mov_b32_e32 v1, v0
	v_mov_b32_e32 v2, v0
	v_mov_b32_e32 v3, v0
	v_mov_b32_e32 v4, v0
	v_mov_b32_e32 v5, v0
	v_mov_b32_e32 v6, v0
	v_mov_b32_e32 v7, v0
	v_mov_b32_e32 v8, v0
	v_mov_b32_e32 v9, v0
	v_mov_b32_e32 v10, v0
	v_mov_b32_e32 v11, v0
	v_mov_b32_e32 v12, v0
	v_mov_b32_e32 v13, v0
	v_mov_b32_e32 v14, v0
	v_mov_b32_e32 v15, v0
	v_mov_b32_e32 v16, v0
	v_mov_b32_e32 v17, v0
	v_mov_b32_e32 v18, v0
	v_mov_b32_e32 v19, v0
	v_mov_b32_e32 v20, v0
	v_mov_b32_e32 v21, v0
	v_mov_b32_e32 v22, v0
	v_mov_b32_e32 v23, v0
	v_mov_b32_e32 v24, v0
	v_mov_b32_e32 v25, v0
	v_mov_b32_e32 v26, v0
	v_mov_b32_e32 v27, v0
	v_mov_b32_e32 v28, v0
	v_mov_b32_e32 v29, v0
	v_mov_b32_e32 v30, v0
	v_mov_b32_e32 v31, v0
	v_mov_b32_e32 v32, v0
	v_mov_b32_e32 v33, v0
	v_mov_b32_e32 v34, v0
	v_mov_b32_e32 v35, v0
	v_mov_b32_e32 v36, v0
	v_mov_b32_e32 v37, v0
	v_mov_b32_e32 v38, v0
	v_mov_b32_e32 v39, v0
	v_mov_b32_e32 v40, v0
	v_mov_b32_e32 v41, v0
	v_mov_b32_e32 v42, v0
	v_mov_b32_e32 v43, v0
	v_mov_b32_e32 v44, v0
	v_mov_b32_e32 v45, v0
	v_mov_b32_e32 v46, v0
	v_mov_b32_e32 v47, v0
	v_mov_b32_e32 v48, v0
	v_mov_b32_e32 v49, v0
	v_mov_b32_e32 v50, v0
	v_mov_b32_e32 v51, v0
	v_mov_b32_e32 v52, v0
	v_mov_b32_e32 v53, v0
	v_mov_b32_e32 v54, v0
	v_mov_b32_e32 v55, v0
	v_mov_b32_e32 v56, v0
	v_mov_b32_e32 v57, v0
	v_mov_b32_e32 v58, v0
	v_mov_b32_e32 v59, v0
	v_mov_b32_e32 v60, v0
	v_mov_b32_e32 v61, v0
	v_mov_b32_e32 v62, v0
	v_mov_b32_e32 v63, v0
	v_mov_b32_e32 v64, v0
	v_mov_b32_e32 v65, v0
	v_mov_b32_e32 v66, v0
	v_mov_b32_e32 v67, v0
	v_mov_b32_e32 v68, v0
	v_mov_b32_e32 v69, v0
	v_mov_b32_e32 v70, v0
	v_mov_b32_e32 v71, v0
	v_mov_b32_e32 v72, v0
	v_mov_b32_e32 v73, v0
	v_mov_b32_e32 v74, v0
	v_mov_b32_e32 v75, v0
	v_mov_b32_e32 v76, v0
	v_mov_b32_e32 v77, v0
	v_mov_b32_e32 v78, v0
	v_mov_b32_e32 v79, v0
	v_mov_b32_e32 v80, v0
	v_mov_b32_e32 v81, v0
	v_mov_b32_e32 v82, v0
	v_mov_b32_e32 v83, v0
	v_mov_b32_e32 v84, v0
	v_mov_b32_e32 v85, v0
	v_mov_b32_e32 v86, v0
	v_mov_b32_e32 v87, v0
	v_mov_b32_e32 v88, v0
	v_mov_b32_e32 v89, v0
	v_mov_b32_e32 v90, v0
	v_mov_b32_e32 v91, v0
	v_mov_b32_e32 v92, v0
	v_mov_b32_e32 v93, v0
	v_mov_b32_e32 v94, v0
	v_mov_b32_e32 v95, v0
	v_mov_b32_e32 v96, v0
	v_mov_b32_e32 v97, v0
	v_mov_b32_e32 v98, v0
	v_mov_b32_e32 v99, v0
	v_mov_b32_e32 v100, v0
	v_mov_b32_e32 v101, v0
	v_mov_b32_e32 v102, v0
	v_mov_b32_e32 v103, v0
	v_mov_b32_e32 v104, v0
	v_mov_b32_e32 v105, v0
	v_mov_b32_e32 v106, v0
	v_mov_b32_e32 v107, v0
	v_mov_b32_e32 v108, v0
	v_mov_b32_e32 v109, v0
	v_mov_b32_e32 v110, v0
	v_mov_b32_e32 v111, v0
	v_mov_b32_e32 v112, v0
	v_mov_b32_e32 v113, v0
	v_mov_b32_e32 v114, v0
	v_mov_b32_e32 v115, v0
	v_mov_b32_e32 v116, v0
	v_mov_b32_e32 v117, v0
	v_mov_b32_e32 v118, v0
	v_mov_b32_e32 v119, v0
	v_mov_b32_e32 v120, v0
	v_mov_b32_e32 v121, v0
	v_mov_b32_e32 v122, v0
	v_mov_b32_e32 v123, v0
	v_mov_b32_e32 v124, v0
	v_mov_b32_e32 v125, v0
	v_mov_b32_e32 v126, v0
	v_mov_b32_e32 v127, v0
	s_barrier
	v_readlane_b32 s65, v254, 13
	v_readlane_b32 s66, v254, 14
	v_readlane_b32 s67, v254, 15
	v_readlane_b32 s70, v254, 18
	v_readlane_b32 s71, v254, 19
	v_readlane_b32 s72, v254, 20
	v_readlane_b32 s73, v254, 21
	v_readlane_b32 s74, v254, 22
	v_readlane_b32 s75, v254, 23
	v_readlane_b32 s76, v254, 24
	v_readlane_b32 s77, v254, 25
	v_readlane_b32 s78, v254, 26
	v_readlane_b32 s79, v254, 27
	s_nop 0
	s_nop 0
	s_nop 0
	s_nop 0
	s_nop 0
	s_nop 0
	s_nop 0
	s_nop 0

.LBB0_811:
	v_add_u32_e32 v155, s53, v17
	v_add_u32_e32 v156, 0x2000, v155
	v_readfirstlane_b32 s58, v155
	v_lshl_add_u64 v[4:5], v[4:5], 0, s[4:5]
	s_mov_b32 m0, s58
	v_readfirstlane_b32 s58, v156
	v_add_u32_e32 v157, 0x8000, v149
	s_waitcnt vmcnt(4)
	s_barrier
	global_load_lds_dwordx4 v[4:5], off
	v_lshl_add_u64 v[4:5], v[6:7], 0, s[4:5]
	s_mov_b32 m0, s58
	v_readfirstlane_b32 s58, v157
	v_add_u32_e32 v158, 0xa000, v149
	global_load_lds_dwordx4 v[4:5], off
	v_lshl_add_u64 v[4:5], v[8:9], 0, s[4:5]
	s_mov_b32 m0, s58
	v_readfirstlane_b32 s58, v158
	v_add_u32_e32 v159, s54, v17
	global_load_lds_dwordx4 v[4:5], off
	v_lshl_add_u64 v[4:5], v[10:11], 0, s[4:5]
	s_mov_b32 m0, s58
	v_readfirstlane_b32 s58, v159
	v_add_u32_e32 v160, 0x2000, v159
	global_load_lds_dwordx4 v[4:5], off
	v_lshl_add_u64 v[4:5], v[12:13], 0, s[4:5]
	s_mov_b32 m0, s58
	v_readfirstlane_b32 s58, v160
	global_load_lds_dwordx4 v[4:5], off
	v_lshl_add_u64 v[4:5], v[14:15], 0, s[4:5]
	s_mov_b32 m0, s58
	v_and_b32_e32 v18, 15, v16
	global_load_lds_dwordx4 v[4:5], off
	v_lshlrev_b32_e32 v5, 2, v16
	v_and_b32_e32 v19, 48, v16
	v_lshlrev_b32_e32 v4, 6, v18
	v_and_b32_e32 v5, 32, v5
	v_bitop3_b32 v4, v4, v5, v19 bitop3:0x36
	v_add_u32_e32 v6, s33, v4
	v_add_u32_e32 v7, s52, v4
	v_add_u32_e32 v8, s53, v4
	v_add_u32_e32 v9, s54, v4
	s_lshl_b32 s61, s17, 13
	v_add_u32_e32 v10, 0, v4
	v_lshlrev_b32_e32 v4, 6, v16
	s_movk_i32 s17, 0x3c0
	v_and_or_b32 v4, v4, s17, v19
	v_xad_u32 v162, v4, v5, 0
	v_lshl_add_u64 v[4:5], s[24:25], 0, v[130:131]
	v_readlane_b32 s64, v254, 12
	v_lshl_add_u64 v[4:5], v[4:5], 0, v[0:1]
	v_readlane_b32 s65, v254, 13
	v_readlane_b32 s72, v254, 20
	v_readlane_b32 s73, v254, 21
	v_lshl_add_u64 v[136:137], s[64:65], 0, v[4:5]
	v_lshl_add_u64 v[4:5], s[24:25], 0, v[134:135]
	v_lshl_add_u64 v[4:5], v[4:5], 0, v[2:3]
	v_lshl_add_u64 v[138:139], s[64:65], 0, v[4:5]
	v_lshl_add_u64 v[4:5], s[34:35], 0, v[130:131]
	v_lshl_add_u64 v[0:1], v[4:5], 0, v[0:1]
	v_lshl_add_u64 v[140:141], s[72:73], 0, v[0:1]
	v_lshl_add_u64 v[0:1], s[34:35], 0, v[134:135]
	s_waitcnt vmcnt(6)
	s_lshl_b32 s58, s0, 6
	v_lshl_add_u64 v[0:1], v[0:1], 0, v[2:3]
	s_and_b32 s60, s58, 0x3000
	v_lshl_add_u64 v[142:143], s[72:73], 0, v[0:1]
	v_mov_b32_e32 v0, 0
	s_or_b32 s17, s61, 0x800
	s_or_b32 s58, s61, 0x1000
	s_or_b32 s59, s61, 0x1800
	s_mov_b32 s34, -2
	s_mov_b64 s[24:25], 0
	v_add_u32_e32 v163, s60, v6
	v_add_u32_e32 v146, s61, v10
	v_add_u32_e32 v161, s60, v7
	v_add_u32_e32 v152, s60, v8
	v_add_u32_e32 v147, s60, v9
	v_mov_b32_e32 v1, v0
	v_mov_b32_e32 v2, v0
	v_mov_b32_e32 v3, v0
	v_mov_b32_e32 v4, v0
	v_mov_b32_e32 v5, v0
	v_mov_b32_e32 v6, v0
	v_mov_b32_e32 v7, v0
	v_mov_b32_e32 v8, v0
	v_mov_b32_e32 v9, v0
	v_mov_b32_e32 v10, v0
	v_mov_b32_e32 v11, v0
	v_mov_b32_e32 v12, v0
	v_mov_b32_e32 v13, v0
	v_mov_b32_e32 v14, v0
	v_mov_b32_e32 v15, v0
	v_mov_b32_e32 v16, v0
	v_mov_b32_e32 v17, v0
	v_mov_b32_e32 v18, v0
	v_mov_b32_e32 v19, v0
	v_mov_b32_e32 v20, v0
	v_mov_b32_e32 v21, v0
	v_mov_b32_e32 v22, v0
	v_mov_b32_e32 v23, v0
	v_mov_b32_e32 v24, v0
	v_mov_b32_e32 v25, v0
	v_mov_b32_e32 v26, v0
	v_mov_b32_e32 v27, v0
	v_mov_b32_e32 v28, v0
	v_mov_b32_e32 v29, v0
	v_mov_b32_e32 v30, v0
	v_mov_b32_e32 v31, v0
	v_mov_b32_e32 v56, v0
	v_mov_b32_e32 v57, v0
	v_mov_b32_e32 v58, v0
	v_mov_b32_e32 v59, v0
	v_mov_b32_e32 v80, v0
	v_mov_b32_e32 v81, v0
	v_mov_b32_e32 v82, v0
	v_mov_b32_e32 v83, v0
	v_mov_b32_e32 v96, v0
	v_mov_b32_e32 v97, v0
	v_mov_b32_e32 v98, v0
	v_mov_b32_e32 v99, v0
	v_mov_b32_e32 v108, v0
	v_mov_b32_e32 v109, v0
	v_mov_b32_e32 v110, v0
	v_mov_b32_e32 v111, v0
	v_mov_b32_e32 v112, v0
	v_mov_b32_e32 v113, v0
	v_mov_b32_e32 v114, v0
	v_mov_b32_e32 v115, v0
	v_mov_b32_e32 v116, v0
	v_mov_b32_e32 v117, v0
	v_mov_b32_e32 v118, v0
	v_mov_b32_e32 v119, v0
	v_mov_b32_e32 v120, v0
	v_mov_b32_e32 v121, v0
	v_mov_b32_e32 v122, v0
	v_mov_b32_e32 v123, v0
	v_mov_b32_e32 v124, v0
	v_mov_b32_e32 v125, v0
	v_mov_b32_e32 v126, v0
	v_mov_b32_e32 v127, v0
	v_mov_b32_e32 v32, v0
	v_mov_b32_e32 v33, v0
	v_mov_b32_e32 v34, v0
	v_mov_b32_e32 v35, v0
	v_mov_b32_e32 v36, v0
	v_mov_b32_e32 v37, v0
	v_mov_b32_e32 v38, v0
	v_mov_b32_e32 v39, v0
	v_mov_b32_e32 v40, v0
	v_mov_b32_e32 v41, v0
	v_mov_b32_e32 v42, v0
	v_mov_b32_e32 v43, v0
	v_mov_b32_e32 v44, v0
	v_mov_b32_e32 v45, v0
	v_mov_b32_e32 v46, v0
	v_mov_b32_e32 v47, v0
	v_mov_b32_e32 v48, v0
	v_mov_b32_e32 v49, v0
	v_mov_b32_e32 v50, v0
	v_mov_b32_e32 v51, v0
	v_mov_b32_e32 v52, v0
	v_mov_b32_e32 v53, v0
	v_mov_b32_e32 v54, v0
	v_mov_b32_e32 v55, v0
	v_mov_b32_e32 v60, v0
	v_mov_b32_e32 v61, v0
	v_mov_b32_e32 v62, v0
	v_mov_b32_e32 v63, v0
	v_mov_b32_e32 v68, v0
	v_mov_b32_e32 v69, v0
	v_mov_b32_e32 v70, v0
	v_mov_b32_e32 v71, v0
	v_mov_b32_e32 v64, v0
	v_mov_b32_e32 v65, v0
	v_mov_b32_e32 v66, v0
	v_mov_b32_e32 v67, v0
	v_mov_b32_e32 v72, v0
	v_mov_b32_e32 v73, v0
	v_mov_b32_e32 v74, v0
	v_mov_b32_e32 v75, v0
	v_mov_b32_e32 v76, v0
	v_mov_b32_e32 v77, v0
	v_mov_b32_e32 v78, v0
	v_mov_b32_e32 v79, v0
	v_mov_b32_e32 v84, v0
	v_mov_b32_e32 v85, v0
	v_mov_b32_e32 v86, v0
	v_mov_b32_e32 v87, v0
	v_mov_b32_e32 v88, v0
	v_mov_b32_e32 v89, v0
	v_mov_b32_e32 v90, v0
	v_mov_b32_e32 v91, v0
	v_mov_b32_e32 v92, v0
	v_mov_b32_e32 v93, v0
	v_mov_b32_e32 v94, v0
	v_mov_b32_e32 v95, v0
	v_mov_b32_e32 v100, v0
	v_mov_b32_e32 v101, v0
	v_mov_b32_e32 v102, v0
	v_mov_b32_e32 v103, v0
	v_mov_b32_e32 v104, v0
	v_mov_b32_e32 v105, v0
	v_mov_b32_e32 v106, v0
	v_mov_b32_e32 v107, v0
	s_barrier
	v_readlane_b32 s66, v254, 14
	v_readlane_b32 s67, v254, 15
	v_readlane_b32 s68, v254, 16
	v_readlane_b32 s69, v254, 17
	v_readlane_b32 s70, v254, 18
	v_readlane_b32 s71, v254, 19
	v_readlane_b32 s74, v254, 22
	v_readlane_b32 s75, v254, 23
	v_readlane_b32 s76, v254, 24
	v_readlane_b32 s77, v254, 25
	v_readlane_b32 s78, v254, 26
	v_readlane_b32 s79, v254, 27
	s_nop 0
	s_nop 0
	s_nop 0
	s_nop 0
	s_nop 0

.LBB0_933:
	v_add_u32_e32 v155, s55, v17
	v_add_u32_e32 v156, 0x2000, v155
	v_readfirstlane_b32 s25, v155
	v_lshl_add_u64 v[4:5], v[4:5], 0, s[4:5]
	s_mov_b32 m0, s25
	v_readfirstlane_b32 s25, v156
	v_add_u32_e32 v157, 0x8000, v148
	s_waitcnt vmcnt(4)
	s_barrier
	global_load_lds_dwordx4 v[4:5], off
	v_lshl_add_u64 v[4:5], v[6:7], 0, s[4:5]
	s_mov_b32 m0, s25
	v_readfirstlane_b32 s25, v157
	v_add_u32_e32 v158, 0xa000, v148
	global_load_lds_dwordx4 v[4:5], off
	v_lshl_add_u64 v[4:5], v[8:9], 0, s[4:5]
	s_mov_b32 m0, s25
	v_readfirstlane_b32 s25, v158
	v_add_u32_e32 v159, s56, v17
	global_load_lds_dwordx4 v[4:5], off
	v_lshl_add_u64 v[4:5], v[10:11], 0, s[4:5]
	s_mov_b32 m0, s25
	v_readfirstlane_b32 s25, v159
	v_add_u32_e32 v160, 0x2000, v159
	global_load_lds_dwordx4 v[4:5], off
	v_lshl_add_u64 v[4:5], v[12:13], 0, s[4:5]
	s_mov_b32 m0, s25
	v_readfirstlane_b32 s25, v160
	global_load_lds_dwordx4 v[4:5], off
	v_lshl_add_u64 v[4:5], v[14:15], 0, s[4:5]
	s_mov_b32 m0, s25
	v_and_b32_e32 v18, 15, v16
	global_load_lds_dwordx4 v[4:5], off
	v_lshlrev_b32_e32 v5, 2, v16
	v_and_b32_e32 v19, 48, v16
	v_lshlrev_b32_e32 v4, 6, v18
	v_and_b32_e32 v5, 32, v5
	v_bitop3_b32 v4, v4, v5, v19 bitop3:0x36
	v_add_u32_e32 v6, s53, v4
	v_add_u32_e32 v7, s54, v4
	v_add_u32_e32 v8, s55, v4
	v_add_u32_e32 v9, s56, v4
	s_lshl_b32 s63, s1, 13
	v_add_u32_e32 v10, 0, v4
	v_lshlrev_b32_e32 v4, 6, v16
	s_movk_i32 s1, 0x3c0
	v_and_or_b32 v4, v4, s1, v19
	v_xad_u32 v161, v4, v5, 0
	v_lshl_add_u64 v[4:5], s[90:91], 0, v[130:131]
	v_readlane_b32 s64, v254, 60
	v_lshl_add_u64 v[4:5], v[4:5], 0, v[0:1]
	v_readlane_b32 s76, v253, 8
	v_readlane_b32 s77, v253, 9
	v_readlane_b32 s65, v254, 61
	v_readlane_b32 s66, v254, 62
	v_lshl_add_u64 v[136:137], s[76:77], 0, v[4:5]
	v_lshl_add_u64 v[4:5], s[90:91], 0, v[134:135]
	v_readlane_b32 s67, v254, 63
	v_readlane_b32 s68, v253, 0
	v_readlane_b32 s69, v253, 1
	v_readlane_b32 s70, v253, 2
	v_readlane_b32 s71, v253, 3
	v_readlane_b32 s72, v253, 4
	v_readlane_b32 s73, v253, 5
	v_readlane_b32 s74, v253, 6
	v_readlane_b32 s75, v253, 7
	v_readlane_b32 s78, v253, 10
	v_readlane_b32 s79, v253, 11
	v_lshl_add_u64 v[4:5], v[4:5], 0, v[2:3]
	v_lshl_add_u64 v[138:139], s[76:77], 0, v[4:5]
	v_lshl_add_u64 v[4:5], s[92:93], 0, v[130:131]
	v_readlane_b32 s64, v254, 12
	v_lshl_add_u64 v[0:1], v[4:5], 0, v[0:1]
	v_readlane_b32 s68, v254, 16
	v_readlane_b32 s69, v254, 17
	s_waitcnt vmcnt(6)
	s_lshl_b32 s25, s59, 6
	s_and_b32 s62, s25, 0x3000
	v_lshl_add_u64 v[140:141], s[68:69], 0, v[0:1]
	v_lshl_add_u64 v[0:1], s[92:93], 0, v[134:135]
	v_lshl_add_u64 v[0:1], v[0:1], 0, v[2:3]
	v_lshl_add_u64 v[142:143], s[68:69], 0, v[0:1]
	v_mov_b32_e32 v0, 0
	s_or_b32 s1, s63, 0x800
	s_or_b32 s25, s63, 0x1000
	s_or_b32 s60, s63, 0x1800
	s_mov_b32 s61, -2
	s_mov_b64 s[90:91], 0
	v_add_u32_e32 v163, s62, v6
	v_add_u32_e32 v147, s63, v10
	v_add_u32_e32 v162, s62, v7
	v_add_u32_e32 v152, s62, v8
	v_add_u32_e32 v150, s62, v9
	v_mov_b32_e32 v1, v0
	v_mov_b32_e32 v2, v0
	v_mov_b32_e32 v3, v0
	v_mov_b32_e32 v4, v0
	v_mov_b32_e32 v5, v0
	v_mov_b32_e32 v6, v0
	v_mov_b32_e32 v7, v0
	v_mov_b32_e32 v8, v0
	v_mov_b32_e32 v9, v0
	v_mov_b32_e32 v10, v0
	v_mov_b32_e32 v11, v0
	v_mov_b32_e32 v12, v0
	v_mov_b32_e32 v13, v0
	v_mov_b32_e32 v14, v0
	v_mov_b32_e32 v15, v0
	v_mov_b32_e32 v16, v0
	v_mov_b32_e32 v17, v0
	v_mov_b32_e32 v18, v0
	v_mov_b32_e32 v19, v0
	v_mov_b32_e32 v20, v0
	v_mov_b32_e32 v21, v0
	v_mov_b32_e32 v22, v0
	v_mov_b32_e32 v23, v0
	v_mov_b32_e32 v24, v0
	v_mov_b32_e32 v25, v0
	v_mov_b32_e32 v26, v0
	v_mov_b32_e32 v27, v0
	v_mov_b32_e32 v28, v0
	v_mov_b32_e32 v29, v0
	v_mov_b32_e32 v30, v0
	v_mov_b32_e32 v31, v0
	v_mov_b32_e32 v32, v0
	v_mov_b32_e32 v33, v0
	v_mov_b32_e32 v34, v0
	v_mov_b32_e32 v35, v0
	v_mov_b32_e32 v36, v0
	v_mov_b32_e32 v37, v0
	v_mov_b32_e32 v38, v0
	v_mov_b32_e32 v39, v0
	v_mov_b32_e32 v40, v0
	v_mov_b32_e32 v41, v0
	v_mov_b32_e32 v42, v0
	v_mov_b32_e32 v43, v0
	v_mov_b32_e32 v44, v0
	v_mov_b32_e32 v45, v0
	v_mov_b32_e32 v46, v0
	v_mov_b32_e32 v47, v0
	v_mov_b32_e32 v48, v0
	v_mov_b32_e32 v49, v0
	v_mov_b32_e32 v50, v0
	v_mov_b32_e32 v51, v0
	v_mov_b32_e32 v52, v0
	v_mov_b32_e32 v53, v0
	v_mov_b32_e32 v54, v0
	v_mov_b32_e32 v55, v0
	v_mov_b32_e32 v56, v0
	v_mov_b32_e32 v57, v0
	v_mov_b32_e32 v58, v0
	v_mov_b32_e32 v59, v0
	v_mov_b32_e32 v60, v0
	v_mov_b32_e32 v61, v0
	v_mov_b32_e32 v62, v0
	v_mov_b32_e32 v63, v0
	v_mov_b32_e32 v64, v0
	v_mov_b32_e32 v65, v0
	v_mov_b32_e32 v66, v0
	v_mov_b32_e32 v67, v0
	v_mov_b32_e32 v68, v0
	v_mov_b32_e32 v69, v0
	v_mov_b32_e32 v70, v0
	v_mov_b32_e32 v71, v0
	v_mov_b32_e32 v72, v0
	v_mov_b32_e32 v73, v0
	v_mov_b32_e32 v74, v0
	v_mov_b32_e32 v75, v0
	v_mov_b32_e32 v76, v0
	v_mov_b32_e32 v77, v0
	v_mov_b32_e32 v78, v0
	v_mov_b32_e32 v79, v0
	v_mov_b32_e32 v80, v0
	v_mov_b32_e32 v81, v0
	v_mov_b32_e32 v82, v0
	v_mov_b32_e32 v83, v0
	v_mov_b32_e32 v84, v0
	v_mov_b32_e32 v85, v0
	v_mov_b32_e32 v86, v0
	v_mov_b32_e32 v87, v0
	v_mov_b32_e32 v88, v0
	v_mov_b32_e32 v89, v0
	v_mov_b32_e32 v90, v0
	v_mov_b32_e32 v91, v0
	v_mov_b32_e32 v92, v0
	v_mov_b32_e32 v93, v0
	v_mov_b32_e32 v94, v0
	v_mov_b32_e32 v95, v0
	v_mov_b32_e32 v96, v0
	v_mov_b32_e32 v97, v0
	v_mov_b32_e32 v98, v0
	v_mov_b32_e32 v99, v0
	v_mov_b32_e32 v100, v0
	v_mov_b32_e32 v101, v0
	v_mov_b32_e32 v102, v0
	v_mov_b32_e32 v103, v0
	v_mov_b32_e32 v104, v0
	v_mov_b32_e32 v105, v0
	v_mov_b32_e32 v106, v0
	v_mov_b32_e32 v107, v0
	v_mov_b32_e32 v108, v0
	v_mov_b32_e32 v109, v0
	v_mov_b32_e32 v110, v0
	v_mov_b32_e32 v111, v0
	v_mov_b32_e32 v112, v0
	v_mov_b32_e32 v113, v0
	v_mov_b32_e32 v114, v0
	v_mov_b32_e32 v115, v0
	v_mov_b32_e32 v116, v0
	v_mov_b32_e32 v117, v0
	v_mov_b32_e32 v118, v0
	v_mov_b32_e32 v119, v0
	v_mov_b32_e32 v120, v0
	v_mov_b32_e32 v121, v0
	v_mov_b32_e32 v122, v0
	v_mov_b32_e32 v123, v0
	v_mov_b32_e32 v124, v0
	v_mov_b32_e32 v125, v0
	v_mov_b32_e32 v126, v0
	v_mov_b32_e32 v127, v0
	s_barrier
	v_readlane_b32 s65, v254, 13
	v_readlane_b32 s66, v254, 14
	v_readlane_b32 s67, v254, 15
	v_readlane_b32 s70, v254, 18
	v_readlane_b32 s71, v254, 19
	v_readlane_b32 s72, v254, 20
	v_readlane_b32 s73, v254, 21
	v_readlane_b32 s74, v254, 22
	v_readlane_b32 s75, v254, 23
	v_readlane_b32 s76, v254, 24
	v_readlane_b32 s77, v254, 25
	v_readlane_b32 s78, v254, 26
	v_readlane_b32 s79, v254, 27
	s_nop 0
	s_nop 0
	s_nop 0
	s_nop 0
	s_nop 0
	s_nop 0
	s_nop 0
	s_nop 0
	s_nop 0
	s_nop 0
	s_nop 0

.LBB0_1522:
	v_add_u32_e32 v155, s39, v17
	v_add_u32_e32 v156, 0x2000, v155
	v_readfirstlane_b32 s46, v155
	v_lshl_add_u64 v[4:5], v[4:5], 0, s[4:5]
	s_mov_b32 m0, s46
	v_readfirstlane_b32 s46, v156
	v_add_u32_e32 v157, 0x8000, v148
	s_waitcnt vmcnt(4)
	s_barrier
	global_load_lds_dwordx4 v[4:5], off
	v_lshl_add_u64 v[4:5], v[6:7], 0, s[4:5]
	s_mov_b32 m0, s46
	v_readfirstlane_b32 s46, v157
	v_add_u32_e32 v158, 0xa000, v148
	global_load_lds_dwordx4 v[4:5], off
	v_lshl_add_u64 v[4:5], v[8:9], 0, s[4:5]
	s_mov_b32 m0, s46
	v_readfirstlane_b32 s46, v158
	v_add_u32_e32 v159, s41, v17
	global_load_lds_dwordx4 v[4:5], off
	v_lshl_add_u64 v[4:5], v[10:11], 0, s[4:5]
	s_mov_b32 m0, s46
	v_readfirstlane_b32 s46, v159
	v_add_u32_e32 v160, 0x2000, v159
	global_load_lds_dwordx4 v[4:5], off
	v_lshl_add_u64 v[4:5], v[12:13], 0, s[4:5]
	s_mov_b32 m0, s46
	v_readfirstlane_b32 s46, v160
	global_load_lds_dwordx4 v[4:5], off
	v_lshl_add_u64 v[4:5], v[14:15], 0, s[4:5]
	s_mov_b32 m0, s46
	v_and_b32_e32 v18, 15, v16
	global_load_lds_dwordx4 v[4:5], off
	v_lshlrev_b32_e32 v5, 2, v16
	v_and_b32_e32 v19, 48, v16
	v_lshlrev_b32_e32 v4, 6, v18
	v_and_b32_e32 v5, 32, v5
	v_bitop3_b32 v4, v4, v5, v19 bitop3:0x36
	v_add_u32_e32 v6, s35, v4
	v_add_u32_e32 v7, s38, v4
	v_add_u32_e32 v8, s39, v4
	v_add_u32_e32 v9, s41, v4
	v_add_u32_e32 v10, 0, v4
	v_lshlrev_b32_e32 v4, 6, v16
	v_and_or_b32 v4, v4, s42, v19
	v_xad_u32 v162, v4, v5, 0
	v_lshl_add_u64 v[4:5], s[28:29], 0, v[130:131]
	v_readlane_b32 s56, v254, 12
	v_lshl_add_u64 v[4:5], v[4:5], 0, v[0:1]
	v_readlane_b32 s57, v254, 13
	v_readlane_b32 s64, v254, 20
	v_readlane_b32 s65, v254, 21
	v_lshl_add_u64 v[136:137], s[56:57], 0, v[4:5]
	v_lshl_add_u64 v[4:5], s[28:29], 0, v[134:135]
	v_lshl_add_u64 v[4:5], v[4:5], 0, v[2:3]
	v_lshl_add_u64 v[138:139], s[56:57], 0, v[4:5]
	v_lshl_add_u64 v[4:5], s[30:31], 0, v[130:131]
	v_lshl_add_u64 v[0:1], v[4:5], 0, v[0:1]
	v_lshl_add_u64 v[140:141], s[64:65], 0, v[0:1]
	v_lshl_add_u64 v[0:1], s[30:31], 0, v[134:135]
	s_waitcnt vmcnt(6)
	s_lshl_b32 s46, s0, 6
	v_lshl_add_u64 v[0:1], v[0:1], 0, v[2:3]
	s_and_b32 s48, s46, 0x3000
	s_lshl_b32 s49, s17, 13
	v_lshl_add_u64 v[142:143], s[64:65], 0, v[0:1]
	v_mov_b32_e32 v0, 0
	s_or_b32 s17, s49, 0x800
	s_or_b32 s46, s49, 0x1000
	s_or_b32 s47, s49, 0x1800
	s_mov_b32 s30, -2
	s_mov_b64 s[28:29], 0
	v_add_u32_e32 v163, s48, v6
	v_add_u32_e32 v146, s49, v10
	v_add_u32_e32 v161, s48, v7
	v_add_u32_e32 v152, s48, v8
	v_add_u32_e32 v147, s48, v9
	v_mov_b32_e32 v1, v0
	v_mov_b32_e32 v2, v0
	v_mov_b32_e32 v3, v0
	v_mov_b32_e32 v4, v0
	v_mov_b32_e32 v5, v0
	v_mov_b32_e32 v6, v0
	v_mov_b32_e32 v7, v0
	v_mov_b32_e32 v8, v0
	v_mov_b32_e32 v9, v0
	v_mov_b32_e32 v10, v0
	v_mov_b32_e32 v11, v0
	v_mov_b32_e32 v12, v0
	v_mov_b32_e32 v13, v0
	v_mov_b32_e32 v14, v0
	v_mov_b32_e32 v15, v0
	v_mov_b32_e32 v16, v0
	v_mov_b32_e32 v17, v0
	v_mov_b32_e32 v18, v0
	v_mov_b32_e32 v19, v0
	v_mov_b32_e32 v20, v0
	v_mov_b32_e32 v21, v0
	v_mov_b32_e32 v22, v0
	v_mov_b32_e32 v23, v0
	v_mov_b32_e32 v24, v0
	v_mov_b32_e32 v25, v0
	v_mov_b32_e32 v26, v0
	v_mov_b32_e32 v27, v0
	v_mov_b32_e32 v28, v0
	v_mov_b32_e32 v29, v0
	v_mov_b32_e32 v30, v0
	v_mov_b32_e32 v31, v0
	v_mov_b32_e32 v56, v0
	v_mov_b32_e32 v57, v0
	v_mov_b32_e32 v58, v0
	v_mov_b32_e32 v59, v0
	v_mov_b32_e32 v80, v0
	v_mov_b32_e32 v81, v0
	v_mov_b32_e32 v82, v0
	v_mov_b32_e32 v83, v0
	v_mov_b32_e32 v96, v0
	v_mov_b32_e32 v97, v0
	v_mov_b32_e32 v98, v0
	v_mov_b32_e32 v99, v0
	v_mov_b32_e32 v108, v0
	v_mov_b32_e32 v109, v0
	v_mov_b32_e32 v110, v0
	v_mov_b32_e32 v111, v0
	v_mov_b32_e32 v112, v0
	v_mov_b32_e32 v113, v0
	v_mov_b32_e32 v114, v0
	v_mov_b32_e32 v115, v0
	v_mov_b32_e32 v116, v0
	v_mov_b32_e32 v117, v0
	v_mov_b32_e32 v118, v0
	v_mov_b32_e32 v119, v0
	v_mov_b32_e32 v120, v0
	v_mov_b32_e32 v121, v0
	v_mov_b32_e32 v122, v0
	v_mov_b32_e32 v123, v0
	v_mov_b32_e32 v124, v0
	v_mov_b32_e32 v125, v0
	v_mov_b32_e32 v126, v0
	v_mov_b32_e32 v127, v0
	v_mov_b32_e32 v32, v0
	v_mov_b32_e32 v33, v0
	v_mov_b32_e32 v34, v0
	v_mov_b32_e32 v35, v0
	v_mov_b32_e32 v36, v0
	v_mov_b32_e32 v37, v0
	v_mov_b32_e32 v38, v0
	v_mov_b32_e32 v39, v0
	v_mov_b32_e32 v40, v0
	v_mov_b32_e32 v41, v0
	v_mov_b32_e32 v42, v0
	v_mov_b32_e32 v43, v0
	v_mov_b32_e32 v44, v0
	v_mov_b32_e32 v45, v0
	v_mov_b32_e32 v46, v0
	v_mov_b32_e32 v47, v0
	v_mov_b32_e32 v48, v0
	v_mov_b32_e32 v49, v0
	v_mov_b32_e32 v50, v0
	v_mov_b32_e32 v51, v0
	v_mov_b32_e32 v52, v0
	v_mov_b32_e32 v53, v0
	v_mov_b32_e32 v54, v0
	v_mov_b32_e32 v55, v0
	v_mov_b32_e32 v60, v0
	v_mov_b32_e32 v61, v0
	v_mov_b32_e32 v62, v0
	v_mov_b32_e32 v63, v0
	v_mov_b32_e32 v68, v0
	v_mov_b32_e32 v69, v0
	v_mov_b32_e32 v70, v0
	v_mov_b32_e32 v71, v0
	v_mov_b32_e32 v64, v0
	v_mov_b32_e32 v65, v0
	v_mov_b32_e32 v66, v0
	v_mov_b32_e32 v67, v0
	v_mov_b32_e32 v72, v0
	v_mov_b32_e32 v73, v0
	v_mov_b32_e32 v74, v0
	v_mov_b32_e32 v75, v0
	v_mov_b32_e32 v76, v0
	v_mov_b32_e32 v77, v0
	v_mov_b32_e32 v78, v0
	v_mov_b32_e32 v79, v0
	v_mov_b32_e32 v84, v0
	v_mov_b32_e32 v85, v0
	v_mov_b32_e32 v86, v0
	v_mov_b32_e32 v87, v0
	v_mov_b32_e32 v88, v0
	v_mov_b32_e32 v89, v0
	v_mov_b32_e32 v90, v0
	v_mov_b32_e32 v91, v0
	v_mov_b32_e32 v92, v0
	v_mov_b32_e32 v93, v0
	v_mov_b32_e32 v94, v0
	v_mov_b32_e32 v95, v0
	v_mov_b32_e32 v100, v0
	v_mov_b32_e32 v101, v0
	v_mov_b32_e32 v102, v0
	v_mov_b32_e32 v103, v0
	v_mov_b32_e32 v104, v0
	v_mov_b32_e32 v105, v0
	v_mov_b32_e32 v106, v0
	v_mov_b32_e32 v107, v0
	s_barrier
	v_readlane_b32 s58, v254, 14
	v_readlane_b32 s59, v254, 15
	v_readlane_b32 s60, v254, 16
	v_readlane_b32 s61, v254, 17
	v_readlane_b32 s62, v254, 18
	v_readlane_b32 s63, v254, 19
	v_readlane_b32 s66, v254, 22
	v_readlane_b32 s67, v254, 23
	v_readlane_b32 s68, v254, 24
	v_readlane_b32 s69, v254, 25
	v_readlane_b32 s70, v254, 26
	v_readlane_b32 s71, v254, 27
	s_nop 0
	s_nop 0
	s_nop 0
	s_nop 0
	s_nop 0
	s_nop 0
	s_nop 0
	s_nop 0
	s_nop 0
	s_nop 0
	s_nop 0
	s_nop 0
